# s5_prep for the next layer moved off the s=5 critical path into the idle tails of the w_out (WGs 16-255) and ff2 (WGs 44-59) GEMM phases
# speedup vs baseline: 1.0174x; 1.0086x over previous
; __device__ void run_phase(const Params& p, int ph, LAS unsigned char* lds) {
;     ...
;     case 5: { tail_glu(p, l, lds); S.init(MP - 256, 512, 512, p.nblk, p.bid); pg8::gemm_phase(lds, pg8::Gemm{proj + C_U, W + W_GLU, MP - 256, 512, 512, NPROJ, nullptr, nullptr}, S, EpiGlu{proj, p.b_glu + (size_t)l * 512}); }
;         if (l + 1 < DEPTH) for (int it = p.bid; it < 256; it += p.nblk) s5_prep_item(p, l + 1, it, ldsf);
;         break;
;     ...
;         break;
;     case 10: { S.init(MP, 1024, DFF, p.nblk, p.bid, 11); pg8::gemm_phase(lds, pg8::Gemm{proj, W + W_FF2, MP, 1024, DFF, DFF, nullptr, nullptr}, S, EpiRes{hres, p.dry ? 0.f : 1.f, (float*)(p.ws + WS_PART), ssq1}); }
;         break;
.LBB0_178:
	s_cmp_eq_u32 s26, 10
	s_cbranch_scc0 .Lprep10_no
	s_and_b64 vcc, exec, s[78:79]
	s_cbranch_vccz .Lprep10_no
	v_readlane_b32 s44, v253, 42
	s_nop 0
	s_cmp_lt_u32 s44, 44
	s_cbranch_scc1 .Lprep10_no
	s_cmp_gt_u32 s44, 59
	s_cbranch_scc1 .Lprep10_no
	s_add_i32 s44, s44, 196
	s_mov_b32 s29, s44
	s_branch .Lprep_entry

; __device__ void run_phase(const Params& p, int ph, LAS unsigned char* lds) {
;     ...
;         if (l + 1 < DEPTH) for (int it = p.bid; it < 256; it += p.nblk) s5_prep_item(p, l + 1, it, ldsf);
;     ...
;     case 7: { S.init(MP, 1024, 1024, p.nblk, p.bid, 4); pg8::gemm_phase(lds, pg8::Gemm{z, W + W_OUT, MP, 1024, 1024, 1024, nullptr, nullptr}, S, EpiRes{hres, p.dry ? 0.f : 1.f, (float*)(p.ws + WS_PART), ssq2}); }
;         break;
.LBB0_233:
	s_and_b64 vcc, exec, s[78:79]
	s_cbranch_vccz .Lprep7_no
	v_readlane_b32 s44, v253, 42
	s_nop 0
	s_cmp_lt_u32 s44, 16
	s_cbranch_scc1 .Lprep7_no
	s_add_i32 s44, s44, -16
	s_mov_b32 s29, s44
	s_branch .Lprep_entry

; __device__ __forceinline__ int otid() { int t = threadIdx.x; asm volatile("" : "+v"(t)); return t; }
; __device__ void s5_prep_item(const Params& p, int l, int gi, float* lds) {
;     const int g = gi >> 3, part = gi & 7;
;     __syncthreads();
;     float* ap_re = lds;
;     float* ap_im = ap_re + 17 * 64;
;     float* bb_re = ap_im + 17 * 64;
;     float* bb_im = bb_re + 1024;
;     float* cc_re = bb_im + 1024;
;     float* cc_im = cc_re + 1024;
;     float* Kd = cc_im + 1024;
;     const int t = otid();
;     const size_t lg = (size_t)l * 32 + g;
; __device__ void run_phase(const Params& p, int ph, LAS unsigned char* lds) {
;     ...
;         if (l + 1 < DEPTH) for (int it = p.bid; it < 256; it += p.nblk) s5_prep_item(p, l + 1, it, ldsf);
.LBB0_392:
	s_mov_b64 s[14:15], 0
	s_andn2_b64 vcc, exec, s[14:15]
	s_mov_b32 s29, s44
	s_cbranch_vccnz .LBB0_441
.Lprep_entry:
	s_lshl_b64 s[14:15], s[72:73], 5
	s_add_u32 s18, s36, 0x1d8f0000
	s_addc_u32 s19, s37, 0
	s_mov_b32 s64, s29
	s_add_u32 s29, s36, 0x1d6f0000
	v_readlane_b32 s48, v252, 0
	s_addc_u32 s30, s37, 0
	s_lshl_b64 s[40:41], s[10:11], 17
	v_readlane_b32 s50, v252, 2
	v_readlane_b32 s51, v252, 3
	s_add_u32 s22, s50, s40
	s_addc_u32 s23, s51, s41
	s_add_u32 s50, s22, 0x20000
	v_readlane_b32 s52, v252, 4
	s_addc_u32 s51, s23, 0
	v_readlane_b32 s53, v252, 5
	s_add_u32 s22, s52, s40
	s_addc_u32 s23, s53, s41
	s_add_u32 s52, s22, 0x20000
	s_addc_u32 s53, s23, 0
	v_readlane_b32 s49, v252, 1
	s_add_u32 s46, s36, 0x1e8c4800
	s_addc_u32 s47, s37, 0
	s_mov_b32 s48, 0
	s_mov_b32 s49, s64
	s_mov_b64 s[4:5], 0x800
	v_readlane_b32 s54, v252, 6
	v_readlane_b32 s55, v252, 7
	v_readlane_b32 s56, v252, 8
	v_readlane_b32 s57, v252, 9
	v_readlane_b32 s58, v252, 10
	v_readlane_b32 s59, v252, 11
	v_readlane_b32 s60, v252, 12
	v_readlane_b32 s61, v252, 13
	v_readlane_b32 s62, v252, 14
	v_readlane_b32 s63, v252, 15
	s_branch .LBB0_395
